# v34 plus next-pair prefetch, DPP row-rotation reduction instead of ds_bpermute in the q/k loop, conv-loop work-item remap
# speedup vs baseline: 1.0045x; 1.0045x over previous
; __device__ __forceinline__ unsigned cvtpk(float lo, float hi) { unsigned r; asm volatile("v_cvt_pk_bf16_f32 %0, %1, %2" : "=v"(r) : "v"(lo), "v"(hi)); return r; }
; __device__ __forceinline__ void ew_phase(const Params& p, int l) {
;     ...
;             float ss = 0.f;
; #pragma unroll
;             for (int q = 0; q < 4; ++q) ss += a[q] * a[q] + b[q] * b[q];
; #pragma unroll
;             for (int o = 8; o >= 1; o >>= 1) ss += __shfl_xor(ss, o);
;             const float rstd = rsqrtf(ss * (1.0f / 128.0f) + EPS);
; #pragma unroll
;             for (int q = 0; q < 4; ++q) { a[q] = a[q] * rstd * ga[q]; b[q] = b[q] * rstd * gb[q]; }
;             if (row >= CTX) { const int tk = row - CTX, pos = (t & 8) ? (tk & 63) : (tk >> 6);
;                 const f32x4 r01 = *(const f32x4*)(rope + pos * 32 + fi), r23 = *(const f32x4*)(rope + pos * 32 + fi + 2);
;                 const float cs[4] = {r01[0], r01[2], r23[0], r23[2]}, sn[4] = {r01[1], r01[3], r23[1], r23[3]};
; #pragma unroll
;                 for (int q = 0; q < 4; ++q) { const float x0 = a[q], x1 = b[q]; a[q] = x0 * cs[q] - x1 * sn[q]; b[q] = x0 * sn[q] + x1 * cs[q]; } }
;             u32x2 oa, ob; oa.x = cvtpk(a[0], a[1]); oa.y = cvtpk(a[2], a[3]); ob.x = cvtpk(b[0], b[1]); ob.y = cvtpk(b[2], b[3]);
;             *(u32x2*)dst_ = oa; *(u32x2*)(dst_ + 32) = ob;
.LBB0_248:
	s_or_b64 exec, exec, s[16:17]
	v_lshl_add_u64 v[10:11], v[10:11], 0, v[96:97]
	v_cvt_pk_bf16_f32 v12, v20, v23
	v_cvt_pk_bf16_f32 v13, v14, v17
	v_cvt_pk_bf16_f32 v14, v18, v19
	v_cvt_pk_bf16_f32 v15, v24, v25
	v_mov_b32_e32 v96, v119
	s_mov_b32 s0, 0x800000
	v_lshl_add_u64 v[210:211], v[10:11], 0, v[96:97]
	v_lshlrev_b32_e32 v220, 16, v218
	v_and_b32_e32 v221, 0xffff0000, v214
	v_lshlrev_b32_e32 v216, 16, v214
	v_and_b32_e32 v217, 0xffff0000, v218
	v_pk_mul_f32 v[224:225], v[220:221], v[220:221]
	v_lshlrev_b32_e32 v238, 16, v215
	v_and_b32_e32 v239, 0xffff0000, v219
	v_pk_fma_f32 v[224:225], v[216:217], v[216:217], v[224:225]
	v_lshlrev_b32_e32 v214, 16, v219
	v_and_b32_e32 v215, 0xffff0000, v215
	v_pk_mul_f32 v[218:219], v[238:239], v[238:239]
	v_add_f32_e32 v213, v224, v225
	v_pk_fma_f32 v[218:219], v[214:215], v[214:215], v[218:219]
	v_mov_b32_e32 v222, v216
	v_add_f32_e32 v213, v218, v213
	v_add_f32_e32 v213, v219, v213
	v_mov_b32_e32 v223, v221
	v_mov_b32_e32 v236, v232
	v_mov_b32_e32 v237, v229
	v_mov_b32_e32 v229, v233
	s_nop 1
	v_add_f32_dpp v213, v213, v213 row_ror:8 row_mask:0xf bank_mask:0xf
	v_mov_b32_e32 v240, v238
	v_mov_b32_e32 v241, v215
	s_nop 1
	v_add_f32_dpp v213, v213, v213 row_ror:4 row_mask:0xf bank_mask:0xf
	s_nop 1
	v_add_f32_dpp v213, v213, v213 row_ror:2 row_mask:0xf bank_mask:0xf
	s_nop 1
	v_add_f32_dpp v213, v213, v213 row_ror:1 row_mask:0xf bank_mask:0xf
	v_fmamk_f32 v213, v213, 0x3c000000, v193
	v_cmp_gt_f32_e64 s[0:1], s0, v213
	v_mul_f32_e32 v218, 0x4b800000, v213
	s_nop 0
	v_cndmask_b32_e64 v213, v213, v218, s[0:1]
	v_rsq_f32_e32 v213, v213
	s_nop 0
	v_mul_f32_e32 v218, 0x45800000, v213
	v_cndmask_b32_e64 v224, v213, v218, s[0:1]
	v_pk_mul_f32 v[218:219], v[224:225], v[220:221] op_sel_hi:[0,1]
	v_pk_mul_f32 v[216:217], v[224:225], v[216:217] op_sel_hi:[0,1]
	v_pk_mul_f32 v[242:243], v[224:225], v[222:223] op_sel_hi:[0,1]
	v_pk_mul_f32 v[222:223], v[236:237], v[216:217]
	v_pk_mul_f32 v[220:221], v[228:229], v[218:219]
	v_pk_mul_f32 v[214:215], v[224:225], v[214:215] op_sel_hi:[0,1]
	v_pk_mul_f32 v[216:217], v[224:225], v[238:239] op_sel_hi:[0,1]
	v_pk_mul_f32 v[224:225], v[224:225], v[240:241] op_sel_hi:[0,1]
	v_mov_b32_e32 v228, v234
	v_mov_b32_e32 v229, v231
	v_mov_b32_e32 v231, v235
	s_mov_b64 s[0:1], 0x13ff
	v_pk_mul_f32 v[218:219], v[232:233], v[242:243]
	v_pk_mul_f32 v[216:217], v[228:229], v[216:217]
	v_pk_mul_f32 v[214:215], v[230:231], v[214:215]
	v_pk_mul_f32 v[224:225], v[234:235], v[224:225]
	v_cmp_lt_i64_e64 s[0:1], s[0:1], v[2:3]
	s_and_saveexec_b64 s[16:17], s[0:1]
	s_cbranch_execz .Lqk_bjoin
	v_mov_b32_e32 v236, v222
	v_mov_b32_e32 v237, v221
	v_mov_b32_e32 v218, v220
	v_mov_b32_e32 v219, v223
	v_mov_b32_e32 v224, v214
	v_mov_b32_e32 v225, v217
	v_mov_b32_e32 v238, v121
	v_mov_b32_e32 v239, v123
	v_mov_b32_e32 v212, v120
	v_mov_b32_e32 v213, v122
	v_pk_mul_f32 v[236:237], v[236:237], v[238:239]
	s_nop 0
	v_pk_fma_f32 v[212:213], v[218:219], v[212:213], v[236:237] neg_lo:[0,0,1] neg_hi:[0,0,1]
	v_mov_b32_e32 v218, v120
	v_mov_b32_e32 v219, v123
	v_pk_mul_f32 v[218:219], v[222:223], v[218:219]
	v_mov_b32_e32 v222, v121
	v_mov_b32_e32 v223, v122
	v_pk_fma_f32 v[218:219], v[220:221], v[222:223], v[218:219]
	v_mov_b32_e32 v222, v216
	v_mov_b32_e32 v223, v215
	v_mov_b32_e32 v120, v125
	v_mov_b32_e32 v121, v127
	v_mov_b32_e32 v220, v124
	v_mov_b32_e32 v221, v126
	v_pk_mul_f32 v[222:223], v[222:223], v[120:121]
	s_nop 0
	v_pk_fma_f32 v[120:121], v[224:225], v[220:221], v[222:223] neg_lo:[0,0,1] neg_hi:[0,0,1]
	v_mov_b32_e32 v221, v127
	v_pk_mul_f32 v[216:217], v[216:217], v[220:221]
	v_mov_b32_e32 v220, v125
	v_mov_b32_e32 v221, v126
	v_pk_fma_f32 v[224:225], v[214:215], v[220:221], v[216:217]
	v_mov_b32_e32 v220, v212
	v_mov_b32_e32 v223, v213
	v_mov_b32_e32 v214, v120
	v_mov_b32_e32 v217, v121

; __device__ __forceinline__ float bflo(unsigned w) { return __uint_as_float(w << 16); }
; __device__ __forceinline__ float bfhi(unsigned w) { return __uint_as_float(w & 0xffff0000u); }
; __device__ __forceinline__ void ew_phase(const Params& p, int l) {
;     ...
;         for (long it = grp; it < (long)ROWS * 20; it += ngrp) { const int row = (int)(it / 20), head = (int)(it % 20);
;             const bf16_t* src_ = P + (size_t)row * INC + (head < 16 ? OQ + head * 128 : OKK + (head - 16) * 128) + base;
;             bf16_t* dst_ = (head < 16) ? (P + (size_t)row * INC + OQ + head * 128 + base) : (KC + ((size_t)(head - 16) * ROWS + row) * 128 + base);
;             const float* gn = (head < 16 ? p.in[I_QN] : p.in[I_KN]) + (size_t)l * 128 + base;
;             const u32x2 wa = *(const u32x2*)src_, wb = *(const u32x2*)(src_ + 32);
;             const f32x4 ga = *(const f32x4*)gn, gb = *(const f32x4*)(gn + 32);
;             float a[4] = {bflo(wa.x), bfhi(wa.x), bflo(wa.y), bfhi(wa.y)}, b[4] = {bflo(wb.x), bfhi(wb.x), bflo(wb.y), bfhi(wb.y)};
;             float ss = 0.f;
; #pragma unroll
;             for (int q = 0; q < 4; ++q) ss += a[q] * a[q] + b[q] * b[q];
; #pragma unroll
;             for (int o = 8; o >= 1; o >>= 1) ss += __shfl_xor(ss, o);
;             const float rstd = rsqrtf(ss * (1.0f / 128.0f) + EPS);
; #pragma unroll
;             for (int q = 0; q < 4; ++q) { a[q] = a[q] * rstd * ga[q]; b[q] = b[q] * rstd * gb[q]; }
;             if (row >= CTX) { const int tk = row - CTX, pos = (t & 8) ? (tk & 63) : (tk >> 6);
;                 const f32x4 r01 = *(const f32x4*)(rope + pos * 32 + fi), r23 = *(const f32x4*)(rope + pos * 32 + fi + 2);
;                 const float cs[4] = {r01[0], r01[2], r23[0], r23[2]}, sn[4] = {r01[1], r01[3], r23[1], r23[3]};
; #pragma unroll
;                 for (int q = 0; q < 4; ++q) { const float x0 = a[q], x1 = b[q]; a[q] = x0 * cs[q] - x1 * sn[q]; b[q] = x0 * sn[q] + x1 * cs[q]; } }
.LBB0_251:
	s_or_b64 exec, exec, s[16:17]
	v_readlane_b32 s0, v245, 45
	v_lshlrev_b32_e32 v96, 1, v4
	v_readlane_b32 s1, v245, 46
	v_lshl_add_u64 v[14:15], v[14:15], 0, v[96:97]
	s_nop 0
	v_lshl_add_u64 v[16:17], v[18:19], 0, s[0:1]
	v_lshlrev_b32_e32 v18, 2, v4
	v_mov_b32_e32 v19, v97
	v_lshl_add_u64 v[16:17], v[16:17], 0, v[18:19]
	global_load_dwordx4 v[28:31], v[16:17], off
	global_load_dwordx4 v[32:35], v[16:17], off offset:128
	global_load_dwordx4 v[228:231], v[16:17], off
	global_load_dwordx4 v[232:235], v[16:17], off offset:128
	s_mov_b64 s[98:99], 0x13ff
	v_cmp_lt_i64_e64 s[98:99], s[98:99], v[2:3]
	s_and_saveexec_b64 s[100:101], s[98:99]
	v_add_u32_e32 v209, 0xffffff00, v12
	v_and_b32_e32 v208, 63, v12
	v_lshrrev_b32_e32 v209, 6, v209
	v_cndmask_b32_e32 v208, v208, v209, vcc
	v_lshlrev_b32_e32 v208, 5, v208
	v_mov_b32_e32 v209, v97
	v_lshl_add_u64 v[208:209], v[208:209], 3, v[6:7]
	flat_load_dwordx4 v[200:203], v[208:209]
	flat_load_dwordx4 v[204:207], v[208:209] offset:16
	flat_load_dwordx4 v[120:123], v[208:209]
	flat_load_dwordx4 v[124:127], v[208:209] offset:16
	s_mov_b64 exec, s[100:101]
	s_mov_b32 s0, 0x800000
	s_waitcnt vmcnt(0) lgkmcnt(0)
	v_mov_b32_e32 v18, v86
	v_mov_b32_e32 v19, v87
	v_mov_b32_e32 v14, v88
	v_mov_b32_e32 v15, v89
	v_mov_b32_e32 v218, v90
	v_mov_b32_e32 v219, v91
	v_mov_b32_e32 v214, v92
	v_mov_b32_e32 v215, v93
	v_readlane_b32 s98, v246, 23
	s_nop 3
	s_lshl_b32 s98, s98, 1
	v_add_u32_e32 v130, s98, v2
	v_min_u32_e32 v130, 0x293fe, v130
	s_mov_b32 s99, 0xcccccccd
	v_mul_hi_u32 v131, v130, s99
	v_lshrrev_b32_e32 v131, 4, v131
	v_lshlrev_b32_e32 v132, 7, v130
	v_mul_u32_u24_e32 v135, 0xa00, v131
	v_sub_u32_e32 v132, v132, v135
	v_mul_u32_u24_e32 v135, 0x8800, v131
	v_add_u32_e32 v132, v132, v4
	v_lshl_add_u32 v136, v132, 1, v135
	v_mov_b32_e32 v137, 0
	v_lshl_add_u64 v[136:137], s[8:9], 0, v[136:137]
	flat_load_dwordx2 v[86:87], v[136:137]
	flat_load_dwordx2 v[88:89], v[136:137] offset:64
	flat_load_dwordx2 v[90:91], v[136:137] offset:256
	flat_load_dwordx2 v[92:93], v[136:137] offset:320
	v_lshlrev_b32_e32 v20, 16, v18
	v_and_b32_e32 v21, 0xffff0000, v14
	v_lshlrev_b32_e32 v16, 16, v14
	v_and_b32_e32 v17, 0xffff0000, v18
	v_pk_mul_f32 v[24:25], v[20:21], v[20:21]
	v_lshlrev_b32_e32 v38, 16, v15
	v_and_b32_e32 v39, 0xffff0000, v19
	v_pk_fma_f32 v[24:25], v[16:17], v[16:17], v[24:25]
	v_lshlrev_b32_e32 v14, 16, v19
	v_and_b32_e32 v15, 0xffff0000, v15
	v_pk_mul_f32 v[18:19], v[38:39], v[38:39]
	v_add_f32_e32 v13, v24, v25
	v_pk_fma_f32 v[18:19], v[14:15], v[14:15], v[18:19]
	v_mov_b32_e32 v22, v16
	v_add_f32_e32 v13, v18, v13
	v_add_f32_e32 v13, v19, v13
	v_mov_b32_e32 v23, v21
	v_mov_b32_e32 v36, v32
	v_mov_b32_e32 v37, v29
	v_mov_b32_e32 v29, v33
	s_nop 1
	v_add_f32_dpp v13, v13, v13 row_ror:8 row_mask:0xf bank_mask:0xf
	v_mov_b32_e32 v40, v38
	v_mov_b32_e32 v41, v15
	s_nop 1
	v_add_f32_dpp v13, v13, v13 row_ror:4 row_mask:0xf bank_mask:0xf
	s_nop 1
	v_add_f32_dpp v13, v13, v13 row_ror:2 row_mask:0xf bank_mask:0xf
	s_nop 1
	v_add_f32_dpp v13, v13, v13 row_ror:1 row_mask:0xf bank_mask:0xf
	v_fmamk_f32 v13, v13, 0x3c000000, v193
	v_cmp_gt_f32_e64 s[0:1], s0, v13
	v_mul_f32_e32 v18, 0x4b800000, v13
	s_nop 0
	v_cndmask_b32_e64 v13, v13, v18, s[0:1]
	v_rsq_f32_e32 v13, v13
	s_nop 0
	v_mul_f32_e32 v18, 0x45800000, v13
	v_cndmask_b32_e64 v24, v13, v18, s[0:1]
	v_pk_mul_f32 v[18:19], v[24:25], v[20:21] op_sel_hi:[0,1]
	v_pk_mul_f32 v[16:17], v[24:25], v[16:17] op_sel_hi:[0,1]
	v_pk_mul_f32 v[42:43], v[24:25], v[22:23] op_sel_hi:[0,1]
	v_pk_mul_f32 v[22:23], v[36:37], v[16:17]
	v_pk_mul_f32 v[20:21], v[28:29], v[18:19]
	v_pk_mul_f32 v[14:15], v[24:25], v[14:15] op_sel_hi:[0,1]
	v_pk_mul_f32 v[16:17], v[24:25], v[38:39] op_sel_hi:[0,1]
	v_pk_mul_f32 v[24:25], v[24:25], v[40:41] op_sel_hi:[0,1]
	v_mov_b32_e32 v28, v34
	v_mov_b32_e32 v29, v31
	v_mov_b32_e32 v31, v35
	s_mov_b64 s[0:1], 0x13ff
	v_pk_mul_f32 v[18:19], v[32:33], v[42:43]
	v_pk_mul_f32 v[16:17], v[28:29], v[16:17]
	v_pk_mul_f32 v[14:15], v[30:31], v[14:15]
	v_pk_mul_f32 v[24:25], v[34:35], v[24:25]
	v_cmp_lt_i64_e64 s[0:1], s[0:1], v[2:3]
	s_and_saveexec_b64 s[16:17], s[0:1]
	s_cbranch_execz .LBB0_248
	v_mov_b32_e32 v36, v22
	v_mov_b32_e32 v37, v21
	v_mov_b32_e32 v18, v20
	v_mov_b32_e32 v19, v23
	v_mov_b32_e32 v24, v14
	v_mov_b32_e32 v25, v17
	s_waitcnt vmcnt(0) lgkmcnt(0)
	v_mov_b32_e32 v38, v201
	v_mov_b32_e32 v39, v203
	v_mov_b32_e32 v12, v200
	v_mov_b32_e32 v13, v202
	v_pk_mul_f32 v[36:37], v[36:37], v[38:39]
	s_nop 0
	v_pk_fma_f32 v[12:13], v[18:19], v[12:13], v[36:37] neg_lo:[0,0,1] neg_hi:[0,0,1]
	v_mov_b32_e32 v18, v200
	v_mov_b32_e32 v19, v203
	v_pk_mul_f32 v[18:19], v[22:23], v[18:19]
	v_mov_b32_e32 v22, v201
	v_mov_b32_e32 v23, v202
	v_pk_fma_f32 v[18:19], v[20:21], v[22:23], v[18:19]
	v_mov_b32_e32 v22, v16
	v_mov_b32_e32 v23, v15
	v_mov_b32_e32 v200, v205
	v_mov_b32_e32 v201, v207
	v_mov_b32_e32 v20, v204
	v_mov_b32_e32 v21, v206
	v_pk_mul_f32 v[22:23], v[22:23], v[200:201]
	s_nop 0
	v_pk_fma_f32 v[200:201], v[24:25], v[20:21], v[22:23] neg_lo:[0,0,1] neg_hi:[0,0,1]
	v_mov_b32_e32 v21, v207
	v_pk_mul_f32 v[16:17], v[16:17], v[20:21]
	v_mov_b32_e32 v20, v205
	v_mov_b32_e32 v21, v206
	v_pk_fma_f32 v[24:25], v[14:15], v[20:21], v[16:17]
	v_mov_b32_e32 v20, v12
	v_mov_b32_e32 v23, v13
	v_mov_b32_e32 v14, v200
	v_mov_b32_e32 v17, v201
	s_branch .LBB0_248
